# select_rows histogram bin: v_floor_f32 + v_cvt_i32_f32 fused into v_cvt_flr_i32_f32 (80 fewer VALU ops)
# speedup vs baseline: 1.0093x; 1.0023x over previous
; #define LAS __attribute__((address_space(3)))
; #define GAS __attribute__((address_space(1)))
; __device__ __forceinline__ unsigned skey_of(float f) { const unsigned u = __float_as_uint(f); return u ^ ((unsigned)((int)u >> 31) | 0x80000000u); }
; template <int NJ>
; __device__ __forceinline__ void select_rows(const GAS float* sr0, GAS unsigned long long* mb0, LAS unsigned* hist, LAS unsigned* kbuf, int ntl, int lane) {
;     ...
;     for (int rr = 0; rr < 8; ++rr) {
;         const GAS float* srow = sr0 + (size_t)rr * SEQ;
;         float fv[NJ];
; #pragma unroll
;         for (int j = 0; j < NJ; ++j) fv[j] = srow[64 * j];
;         { unsigned z = 0u; asm volatile("" : "+v"(z));
;           *(LAS u32x4*)(hist + 4 * lane) = (u32x4){z, z, z, z}; if (lane < 2) hist[256 + lane] = z; }
;         __builtin_amdgcn_wave_barrier();
;         unsigned key[NJ];
; #pragma unroll
;         for (int j = 0; j < NJ; ++j) {
;             const float f = fv[j]; const bool ok = (vm >> j) & 1u;
;             key[j] = ok ? skey_of(f) : 0u;
;             const int bk = min(max((int)floorf(f + f) + 128, 0), 255);
;             __hip_atomic_fetch_add(hist + (ok ? bk : 256), 1u, __ATOMIC_RELAXED, __HIP_MEMORY_SCOPE_WORKGROUP);
;         }
.LBB0_382:
	s_lshl_b32 s88, s12, 11
	v_lshl_add_u64 v[2:3], s[88:89], 2, v[8:9]
	s_movk_i32 s0, 0x1000
	s_add_i32 s98, s88, 0x800
	s_mov_b32 s99, s89
	s_waitcnt vmcnt(1)
	v_mov_b32_e32 v45, v51
	v_mov_b32_e32 v10, v52
	v_mov_b32_e32 v11, v53
	v_mov_b32_e32 v12, v54
	v_mov_b32_e32 v13, v55
	v_mov_b32_e32 v14, v56
	v_mov_b32_e32 v15, v57
	v_mov_b32_e32 v16, v58
	v_mov_b32_e32 v17, v59
	v_mov_b32_e32 v18, v60
	v_mov_b32_e32 v19, v61
	v_mov_b32_e32 v20, v62
	v_mov_b32_e32 v21, v63
	v_mov_b32_e32 v22, v64
	v_mov_b32_e32 v23, v65
	v_mov_b32_e32 v24, v66
	v_mov_b32_e32 v25, v67
	v_mov_b32_e32 v26, v68
	v_mov_b32_e32 v27, v69
	v_mov_b32_e32 v28, v70
	v_mov_b32_e32 v29, v71
	v_mov_b32_e32 v30, v72
	v_mov_b32_e32 v31, v73
	v_mov_b32_e32 v32, v74
	v_mov_b32_e32 v33, v75
	v_mov_b32_e32 v34, v76
	v_mov_b32_e32 v35, v77
	v_mov_b32_e32 v36, v78
	v_mov_b32_e32 v37, v79
	v_mov_b32_e32 v42, v80
	v_mov_b32_e32 v43, v81
	v_mov_b32_e32 v44, v82
	v_lshl_add_u64 v[84:85], s[98:99], 2, v[8:9]
	v_add_co_u32_e32 v86, vcc, 0x1000, v84
	s_nop 1
	v_addc_co_u32_e32 v87, vcc, 0, v85, vcc
	global_load_dword v51, v[84:85], off
	global_load_dword v52, v[84:85], off offset:256
	global_load_dword v53, v[84:85], off offset:512
	global_load_dword v54, v[84:85], off offset:768
	global_load_dword v55, v[84:85], off offset:1024
	global_load_dword v56, v[84:85], off offset:1280
	global_load_dword v57, v[84:85], off offset:1536
	global_load_dword v58, v[84:85], off offset:1792
	global_load_dword v59, v[84:85], off offset:2048
	global_load_dword v60, v[84:85], off offset:2304
	global_load_dword v61, v[84:85], off offset:2560
	global_load_dword v62, v[84:85], off offset:2816
	global_load_dword v63, v[84:85], off offset:3072
	global_load_dword v64, v[84:85], off offset:3328
	global_load_dword v65, v[84:85], off offset:3584
	global_load_dword v66, v[84:85], off offset:3840
	global_load_dword v67, v[86:87], off
	global_load_dword v68, v[86:87], off offset:256
	global_load_dword v69, v[86:87], off offset:512
	global_load_dword v70, v[86:87], off offset:768
	global_load_dword v71, v[86:87], off offset:1024
	global_load_dword v72, v[86:87], off offset:1280
	global_load_dword v73, v[86:87], off offset:1536
	global_load_dword v74, v[86:87], off offset:1792
	global_load_dword v75, v[86:87], off offset:2048
	global_load_dword v76, v[86:87], off offset:2304
	global_load_dword v77, v[86:87], off offset:2560
	global_load_dword v78, v[86:87], off offset:2816
	global_load_dword v79, v[86:87], off offset:3072
	global_load_dword v80, v[86:87], off offset:3328
	global_load_dword v81, v[86:87], off offset:3584
	global_load_dword v82, v[86:87], off offset:3840
	v_mov_b32_e32 v2, 0
	s_nop 0
	v_mov_b32_e32 v3, v2
	v_mov_b32_e32 v4, v2
	v_mov_b32_e32 v5, v2
	ds_write_b128 v7, v[2:5]
	s_and_saveexec_b64 s[0:1], s[74:75]
	v_add_u32_e32 v3, v7, v38
	ds_write_b32 v3, v2 offset:1024
	s_or_b64 exec, exec, s[0:1]
	v_add_f32_e32 v2, v45, v45
	v_cvt_flr_i32_f32_e32 v2, v2
	v_add_f32_e32 v3, v10, v10
	v_cvt_flr_i32_f32_e32 v3, v3
	v_max_i32_e32 v2, 0xffffff80, v2
	v_add_u32_e32 v2, 0x80, v2
	v_min_u32_e32 v2, 0xff, v2
	v_cndmask_b32_e64 v2, v2, v226, s[94:95]
	v_lshl_add_u32 v2, v2, 2, s6
	ds_add_u32 v2, v223
	v_max_i32_e32 v2, 0xffffff80, v3
	v_add_f32_e32 v3, v11, v11
	v_add_u32_e32 v2, 0x80, v2
	v_cvt_flr_i32_f32_e32 v3, v3
	v_min_u32_e32 v2, 0xff, v2
	v_cndmask_b32_e64 v2, v2, v226, s[14:15]
	v_lshl_add_u32 v2, v2, 2, s6
	ds_add_u32 v2, v223
	v_max_i32_e32 v2, 0xffffff80, v3
	v_add_f32_e32 v3, v12, v12
	v_add_u32_e32 v2, 0x80, v2
	v_cvt_flr_i32_f32_e32 v3, v3
	v_min_u32_e32 v2, 0xff, v2
	v_cndmask_b32_e64 v2, v2, v226, s[16:17]
	v_lshl_add_u32 v2, v2, 2, s6
	ds_add_u32 v2, v223
	v_max_i32_e32 v2, 0xffffff80, v3
	v_add_f32_e32 v3, v13, v13
	v_add_u32_e32 v2, 0x80, v2
	v_cvt_flr_i32_f32_e32 v3, v3
	v_min_u32_e32 v2, 0xff, v2
	v_cndmask_b32_e64 v2, v2, v226, s[18:19]
	v_lshl_add_u32 v2, v2, 2, s6
	ds_add_u32 v2, v223
	v_max_i32_e32 v2, 0xffffff80, v3
	v_add_f32_e32 v3, v14, v14
	v_add_u32_e32 v2, 0x80, v2
	v_cvt_flr_i32_f32_e32 v3, v3
	v_min_u32_e32 v2, 0xff, v2
	v_cndmask_b32_e64 v2, v2, v226, s[24:25]
	v_lshl_add_u32 v2, v2, 2, s6
	ds_add_u32 v2, v223
	v_max_i32_e32 v2, 0xffffff80, v3
	v_add_f32_e32 v3, v15, v15
	v_add_u32_e32 v2, 0x80, v2
	v_cvt_flr_i32_f32_e32 v3, v3
	v_min_u32_e32 v2, 0xff, v2
	v_cndmask_b32_e64 v2, v2, v226, s[26:27]
	v_lshl_add_u32 v2, v2, 2, s6
	ds_add_u32 v2, v223
	v_max_i32_e32 v2, 0xffffff80, v3
	v_add_f32_e32 v3, v16, v16
	v_add_u32_e32 v2, 0x80, v2
	v_cvt_flr_i32_f32_e32 v3, v3
	v_min_u32_e32 v2, 0xff, v2
	v_cndmask_b32_e64 v2, v2, v226, s[28:29]
	v_lshl_add_u32 v2, v2, 2, s6
	ds_add_u32 v2, v223
	v_max_i32_e32 v2, 0xffffff80, v3
	v_add_f32_e32 v3, v17, v17
	v_add_u32_e32 v2, 0x80, v2
	v_cvt_flr_i32_f32_e32 v3, v3
	v_min_u32_e32 v2, 0xff, v2
	v_cndmask_b32_e64 v2, v2, v226, s[30:31]
	v_lshl_add_u32 v2, v2, 2, s6
	ds_add_u32 v2, v223
	v_max_i32_e32 v2, 0xffffff80, v3
	v_add_f32_e32 v3, v18, v18
	v_add_u32_e32 v2, 0x80, v2
	v_cvt_flr_i32_f32_e32 v3, v3
	v_min_u32_e32 v2, 0xff, v2
	v_cndmask_b32_e64 v2, v2, v226, s[34:35]
	v_lshl_add_u32 v2, v2, 2, s6
	ds_add_u32 v2, v223
	v_max_i32_e32 v2, 0xffffff80, v3
	v_add_f32_e32 v3, v19, v19
	v_add_u32_e32 v2, 0x80, v2
	v_cvt_flr_i32_f32_e32 v3, v3
	v_min_u32_e32 v2, 0xff, v2
	v_cndmask_b32_e64 v2, v2, v226, s[36:37]
	v_lshl_add_u32 v2, v2, 2, s6
	ds_add_u32 v2, v223
	v_max_i32_e32 v2, 0xffffff80, v3
	v_add_f32_e32 v3, v20, v20
	v_add_u32_e32 v2, 0x80, v2
	v_cvt_flr_i32_f32_e32 v3, v3
	v_min_u32_e32 v2, 0xff, v2
	v_cndmask_b32_e64 v2, v2, v226, s[38:39]
	v_lshl_add_u32 v2, v2, 2, s6
	ds_add_u32 v2, v223
	v_max_i32_e32 v2, 0xffffff80, v3
; #define LAS __attribute__((address_space(3)))
; template <int NJ>
; __device__ __forceinline__ void select_rows(const GAS float* sr0, GAS unsigned long long* mb0, LAS unsigned* hist, LAS unsigned* kbuf, int ntl, int lane) {
;     ...
;             const int bk = min(max((int)floorf(f + f) + 128, 0), 255);
;             __hip_atomic_fetch_add(hist + (ok ? bk : 256), 1u, __ATOMIC_RELAXED, __HIP_MEMORY_SCOPE_WORKGROUP);
;         }
;         __builtin_amdgcn_wave_barrier();
;         asm volatile("s_waitcnt lgkmcnt(0)" ::: "memory");
;         unsigned B, rem, C;
;         {
;             const u32x4 hv = *(const LAS u32x4*)(hist + 4 * lane);
;             const unsigned s4 = hv.x + hv.y + hv.z + hv.w;
;             unsigned S = s4;
; #pragma unroll
;             for (int off = 1; off < 64; off <<= 1) { const unsigned n = __shfl_down(S, off); if (lane + off < 64) S += n; }
;             const unsigned excl = S - s4;
;             const bool mine = (excl < 256u) && (256u <= S);
;             unsigned dl, above, cnt, c = excl;
;             if (c + hv.w >= 256u) { dl = 3; above = c; cnt = hv.w; } else { c += hv.w; if (c + hv.z >= 256u) { dl = 2; above = c; cnt = hv.z; } else { c += hv.z; if (c + hv.y >= 256u) { dl = 1; above = c; cnt = hv.y; } else { c += hv.y; dl = 0; above = c; cnt = hv.x; } } }
	v_add_f32_e32 v3, v21, v21
	v_add_u32_e32 v2, 0x80, v2
	v_cvt_flr_i32_f32_e32 v3, v3
	v_min_u32_e32 v2, 0xff, v2
	v_cndmask_b32_e64 v2, v2, v226, s[40:41]
	v_lshl_add_u32 v2, v2, 2, s6
	ds_add_u32 v2, v223
	v_max_i32_e32 v2, 0xffffff80, v3
	v_add_f32_e32 v3, v22, v22
	v_add_u32_e32 v2, 0x80, v2
	v_cvt_flr_i32_f32_e32 v3, v3
	v_min_u32_e32 v2, 0xff, v2
	v_cndmask_b32_e64 v2, v2, v226, s[42:43]
	v_lshl_add_u32 v2, v2, 2, s6
	ds_add_u32 v2, v223
	v_max_i32_e32 v2, 0xffffff80, v3
	v_add_f32_e32 v3, v23, v23
	v_add_u32_e32 v2, 0x80, v2
	v_cvt_flr_i32_f32_e32 v3, v3
	v_min_u32_e32 v2, 0xff, v2
	v_cndmask_b32_e64 v2, v2, v226, s[44:45]
	v_lshl_add_u32 v2, v2, 2, s6
	ds_add_u32 v2, v223
	v_max_i32_e32 v2, 0xffffff80, v3
	v_add_f32_e32 v3, v24, v24
	v_add_u32_e32 v2, 0x80, v2
	v_cvt_flr_i32_f32_e32 v3, v3
	v_min_u32_e32 v2, 0xff, v2
	v_cndmask_b32_e64 v2, v2, v226, s[46:47]
	v_lshl_add_u32 v2, v2, 2, s6
	ds_add_u32 v2, v223
	v_max_i32_e32 v2, 0xffffff80, v3
	v_add_f32_e32 v3, v25, v25
	v_add_u32_e32 v2, 0x80, v2
	v_cvt_flr_i32_f32_e32 v3, v3
	v_min_u32_e32 v2, 0xff, v2
	v_cndmask_b32_e64 v2, v2, v226, s[48:49]
	v_lshl_add_u32 v2, v2, 2, s6
	ds_add_u32 v2, v223
	v_max_i32_e32 v2, 0xffffff80, v3
	v_add_f32_e32 v3, v26, v26
	v_add_u32_e32 v2, 0x80, v2
	v_cvt_flr_i32_f32_e32 v3, v3
	v_min_u32_e32 v2, 0xff, v2
	v_cndmask_b32_e64 v2, v2, v226, s[50:51]
	v_lshl_add_u32 v2, v2, 2, s6
	ds_add_u32 v2, v223
	v_max_i32_e32 v2, 0xffffff80, v3
	v_add_f32_e32 v3, v27, v27
	v_add_u32_e32 v2, 0x80, v2
	v_cvt_flr_i32_f32_e32 v3, v3
	v_min_u32_e32 v2, 0xff, v2
	v_cndmask_b32_e64 v2, v2, v226, s[52:53]
	v_lshl_add_u32 v2, v2, 2, s6
	ds_add_u32 v2, v223
	v_max_i32_e32 v2, 0xffffff80, v3
	v_add_f32_e32 v3, v28, v28
	v_add_u32_e32 v2, 0x80, v2
	v_cvt_flr_i32_f32_e32 v3, v3
	v_min_u32_e32 v2, 0xff, v2
	v_cndmask_b32_e64 v2, v2, v226, s[54:55]
	v_lshl_add_u32 v2, v2, 2, s6
	ds_add_u32 v2, v223
	v_max_i32_e32 v2, 0xffffff80, v3
	v_add_f32_e32 v3, v29, v29
	v_add_u32_e32 v2, 0x80, v2
	v_cvt_flr_i32_f32_e32 v3, v3
	v_min_u32_e32 v2, 0xff, v2
	v_cndmask_b32_e64 v2, v2, v226, s[64:65]
	v_lshl_add_u32 v2, v2, 2, s6
	ds_add_u32 v2, v223
	v_max_i32_e32 v2, 0xffffff80, v3
	v_add_f32_e32 v3, v30, v30
	v_add_u32_e32 v2, 0x80, v2
	v_cvt_flr_i32_f32_e32 v3, v3
	v_min_u32_e32 v2, 0xff, v2
	v_cndmask_b32_e64 v2, v2, v226, s[66:67]
	v_lshl_add_u32 v2, v2, 2, s6
	ds_add_u32 v2, v223
	v_max_i32_e32 v2, 0xffffff80, v3
	v_add_f32_e32 v3, v31, v31
	v_add_u32_e32 v2, 0x80, v2
	v_cvt_flr_i32_f32_e32 v3, v3
	v_min_u32_e32 v2, 0xff, v2
	v_cndmask_b32_e64 v2, v2, v226, s[70:71]
	v_lshl_add_u32 v2, v2, 2, s6
	ds_add_u32 v2, v223
	v_max_i32_e32 v2, 0xffffff80, v3
	v_add_f32_e32 v3, v32, v32
	v_add_u32_e32 v2, 0x80, v2
	v_cvt_flr_i32_f32_e32 v3, v3
	v_min_u32_e32 v2, 0xff, v2
	v_cndmask_b32_e64 v2, v2, v226, s[72:73]
	v_lshl_add_u32 v2, v2, 2, s6
	ds_add_u32 v2, v223
	v_max_i32_e32 v2, 0xffffff80, v3
	v_add_f32_e32 v3, v33, v33
	v_add_u32_e32 v2, 0x80, v2
	v_cvt_flr_i32_f32_e32 v3, v3
	v_min_u32_e32 v2, 0xff, v2
	v_cndmask_b32_e64 v2, v2, v226, s[76:77]
	v_lshl_add_u32 v2, v2, 2, s6
	ds_add_u32 v2, v223
	v_max_i32_e32 v2, 0xffffff80, v3
	v_add_f32_e32 v3, v34, v34
	v_add_u32_e32 v2, 0x80, v2
	v_cvt_flr_i32_f32_e32 v3, v3
	v_min_u32_e32 v2, 0xff, v2
	v_cndmask_b32_e64 v2, v2, v226, s[78:79]
	v_lshl_add_u32 v2, v2, 2, s6
	ds_add_u32 v2, v223
	v_max_i32_e32 v2, 0xffffff80, v3
	v_add_f32_e32 v3, v35, v35
	v_add_u32_e32 v2, 0x80, v2
	v_cvt_flr_i32_f32_e32 v3, v3
	v_min_u32_e32 v2, 0xff, v2
	v_cndmask_b32_e64 v2, v2, v226, s[84:85]
	v_lshl_add_u32 v2, v2, 2, s6
	ds_add_u32 v2, v223
	v_max_i32_e32 v2, 0xffffff80, v3
	v_add_f32_e32 v3, v36, v36
	v_add_u32_e32 v2, 0x80, v2
	v_cvt_flr_i32_f32_e32 v3, v3
	v_min_u32_e32 v2, 0xff, v2
	v_cndmask_b32_e64 v2, v2, v226, s[90:91]
	v_lshl_add_u32 v2, v2, 2, s6
	ds_add_u32 v2, v223
	v_max_i32_e32 v2, 0xffffff80, v3
	v_add_f32_e32 v3, v37, v37
	v_add_u32_e32 v2, 0x80, v2
	v_cvt_flr_i32_f32_e32 v3, v3
	v_min_u32_e32 v2, 0xff, v2
	v_cndmask_b32_e64 v2, v2, v226, s[92:93]
	v_lshl_add_u32 v2, v2, 2, s6
	ds_add_u32 v2, v223
	v_max_i32_e32 v2, 0xffffff80, v3
	v_add_f32_e32 v3, v42, v42
	v_add_u32_e32 v2, 0x80, v2
	v_cvt_flr_i32_f32_e32 v3, v3
	v_min_u32_e32 v2, 0xff, v2
	v_cndmask_b32_e64 v2, v2, v226, s[8:9]
	v_lshl_add_u32 v2, v2, 2, s6
	ds_add_u32 v2, v223
	v_max_i32_e32 v2, 0xffffff80, v3
	v_add_f32_e32 v3, v43, v43
	v_add_u32_e32 v2, 0x80, v2
	v_cvt_flr_i32_f32_e32 v3, v3
	v_readlane_b32 s0, v254, 33
	v_min_u32_e32 v2, 0xff, v2
	v_readlane_b32 s1, v254, 34
	s_nop 1
	v_cndmask_b32_e64 v2, v2, v226, s[0:1]
	v_lshl_add_u32 v2, v2, 2, s6
	ds_add_u32 v2, v223
	v_max_i32_e32 v2, 0xffffff80, v3
	v_add_f32_e32 v3, v44, v44
	v_add_u32_e32 v2, 0x80, v2
	v_cvt_flr_i32_f32_e32 v3, v3
	v_readlane_b32 s0, v254, 35
	v_min_u32_e32 v2, 0xff, v2
	v_readlane_b32 s1, v254, 36
	s_nop 1
	v_cndmask_b32_e64 v2, v2, v226, s[0:1]
	v_lshl_add_u32 v2, v2, 2, s6
	ds_add_u32 v2, v223
	v_max_i32_e32 v2, 0xffffff80, v3
	v_add_u32_e32 v2, 0x80, v2
	v_readlane_b32 s0, v254, 37
	v_min_u32_e32 v2, 0xff, v2
	v_readlane_b32 s1, v254, 38
	s_nop 1
	v_cndmask_b32_e64 v2, v2, v226, s[0:1]
	v_lshl_add_u32 v2, v2, 2, s6
	ds_add_u32 v2, v223
	s_waitcnt lgkmcnt(0)
	ds_read_b128 v[2:5], v7
	v_readlane_b32 s0, v254, 41
	v_readlane_b32 s1, v254, 42
	s_waitcnt lgkmcnt(0)
	v_add_u32_e32 v46, v2, v3
	v_add3_u32 v47, v46, v4, v5
	v_mov_b32_e32 v46, v47
	s_nop 1
	v_add_u32_dpp v46, v46, v46 row_shr:1 row_mask:0xf bank_mask:0xf bound_ctrl:0
	s_nop 1
	v_add_u32_dpp v46, v46, v46 row_shr:2 row_mask:0xf bank_mask:0xf bound_ctrl:0
	s_nop 1
	v_add_u32_dpp v46, v46, v46 row_shr:4 row_mask:0xf bank_mask:0xf bound_ctrl:0
	s_nop 1
	v_add_u32_dpp v46, v46, v46 row_shr:8 row_mask:0xf bank_mask:0xf bound_ctrl:0
	s_nop 1
	v_add_u32_dpp v46, v46, v46 row_bcast:15 row_mask:0xa bank_mask:0xf
	s_nop 1
	v_add_u32_dpp v46, v46, v46 row_bcast:31 row_mask:0xc bank_mask:0xf
	s_nop 1
	v_readlane_b32 s0, v46, 63
	s_nop 1
	v_sub_u32_e32 v48, s0, v46
	v_add_u32_e32 v46, v48, v47
	v_mov_b32_e32 v47, v48
	v_add_u32_e32 v50, v47, v5
	v_cmp_gt_u32_e32 vcc, s63, v50
	v_mov_b32_e32 v48, 3
	v_mov_b32_e32 v49, v47
	s_and_saveexec_b64 s[0:1], vcc
	s_cbranch_execz .LBB0_388
	v_add_u32_e32 v5, v50, v4
	v_cmp_gt_u32_e32 vcc, s63, v5
	v_mov_b32_e32 v48, 2
	s_and_saveexec_b64 s[2:3], vcc
	v_add_u32_e32 v4, v5, v3
	s_movk_i32 s4, 0xff
	v_cmp_lt_u32_e32 vcc, s4, v4
	s_nop 1
	v_cndmask_b32_e64 v48, 0, 1, vcc
	v_cndmask_b32_e32 v50, v4, v5, vcc
	v_cndmask_b32_e32 v4, v2, v3, vcc
	s_or_b64 exec, exec, s[2:3]
	v_mov_b32_e32 v5, v4
	v_mov_b32_e32 v49, v50

; #define LAS __attribute__((address_space(3)))
; #define GAS __attribute__((address_space(1)))
; __device__ __forceinline__ unsigned skey_of(float f) { const unsigned u = __float_as_uint(f); return u ^ ((unsigned)((int)u >> 31) | 0x80000000u); }
; template <int NJ>
; __device__ __forceinline__ void select_rows(const GAS float* sr0, GAS unsigned long long* mb0, LAS unsigned* hist, LAS unsigned* kbuf, int ntl, int lane) {
;     ...
;     for (int rr = 0; rr < 8; ++rr) {
;         const GAS float* srow = sr0 + (size_t)rr * SEQ;
;         float fv[NJ];
; #pragma unroll
;         for (int j = 0; j < NJ; ++j) fv[j] = srow[64 * j];
;         { unsigned z = 0u; asm volatile("" : "+v"(z));
;           *(LAS u32x4*)(hist + 4 * lane) = (u32x4){z, z, z, z}; if (lane < 2) hist[256 + lane] = z; }
;         __builtin_amdgcn_wave_barrier();
;         unsigned key[NJ];
; #pragma unroll
;         for (int j = 0; j < NJ; ++j) {
;             const float f = fv[j]; const bool ok = (vm >> j) & 1u;
;             key[j] = ok ? skey_of(f) : 0u;
;             const int bk = min(max((int)floorf(f + f) + 128, 0), 255);
;             __hip_atomic_fetch_add(hist + (ok ? bk : 256), 1u, __ATOMIC_RELAXED, __HIP_MEMORY_SCOPE_WORKGROUP);
;         }
.LBB0_533:
	s_lshl_b32 s88, s7, 11
	v_lshl_add_u64 v[2:3], s[88:89], 2, v[8:9]
	global_load_dword v33, v[2:3], off
	global_load_dword v10, v[2:3], off offset:256
	global_load_dword v11, v[2:3], off offset:512
	global_load_dword v12, v[2:3], off offset:768
	global_load_dword v13, v[2:3], off offset:1024
	global_load_dword v14, v[2:3], off offset:1280
	global_load_dword v15, v[2:3], off offset:1536
	global_load_dword v16, v[2:3], off offset:1792
	global_load_dword v17, v[2:3], off offset:2048
	global_load_dword v18, v[2:3], off offset:2304
	global_load_dword v19, v[2:3], off offset:2560
	global_load_dword v20, v[2:3], off offset:2816
	global_load_dword v21, v[2:3], off offset:3072
	global_load_dword v22, v[2:3], off offset:3328
	global_load_dword v23, v[2:3], off offset:3584
	global_load_dword v24, v[2:3], off offset:3840
	s_movk_i32 s0, 0x1000
	v_add_co_u32_e32 v2, vcc, s0, v2
	s_nop 1
	v_addc_co_u32_e32 v3, vcc, 0, v3, vcc
	global_load_dword v25, v[2:3], off
	global_load_dword v26, v[2:3], off offset:256
	global_load_dword v27, v[2:3], off offset:512
	global_load_dword v28, v[2:3], off offset:768
	global_load_dword v29, v[2:3], off offset:1024
	global_load_dword v30, v[2:3], off offset:1280
	global_load_dword v31, v[2:3], off offset:1536
	global_load_dword v32, v[2:3], off offset:1792
	v_mov_b32_e32 v2, 0
	s_nop 0
	v_mov_b32_e32 v3, v2
	v_mov_b32_e32 v4, v2
	v_mov_b32_e32 v5, v2
	ds_write_b128 v7, v[2:5]
	s_and_saveexec_b64 s[0:1], s[74:75]
	v_add_u32_e32 v3, v7, v38
	ds_write_b32 v3, v2 offset:1024
	s_or_b64 exec, exec, s[0:1]
	s_waitcnt vmcnt(23)
	v_add_f32_e32 v2, v33, v33
	v_cvt_flr_i32_f32_e32 v2, v2
	s_waitcnt vmcnt(22)
	v_add_f32_e32 v3, v10, v10
	v_cvt_flr_i32_f32_e32 v3, v3
	v_max_i32_e32 v2, 0xffffff80, v2
	v_add_u32_e32 v2, 0x80, v2
	v_min_u32_e32 v2, 0xff, v2
	v_cndmask_b32_e64 v2, v2, v226, s[14:15]
	v_lshl_add_u32 v2, v2, 2, s6
	ds_add_u32 v2, v223
	v_max_i32_e32 v2, 0xffffff80, v3
	s_waitcnt vmcnt(21)
	v_add_f32_e32 v3, v11, v11
	v_add_u32_e32 v2, 0x80, v2
	v_cvt_flr_i32_f32_e32 v3, v3
	v_min_u32_e32 v2, 0xff, v2
	v_cndmask_b32_e64 v2, v2, v226, s[16:17]
	v_lshl_add_u32 v2, v2, 2, s6
	ds_add_u32 v2, v223
	v_max_i32_e32 v2, 0xffffff80, v3
	s_waitcnt vmcnt(20)
	v_add_f32_e32 v3, v12, v12
	v_add_u32_e32 v2, 0x80, v2
	v_cvt_flr_i32_f32_e32 v3, v3
	v_min_u32_e32 v2, 0xff, v2
	v_cndmask_b32_e64 v2, v2, v226, s[18:19]
	v_lshl_add_u32 v2, v2, 2, s6
	ds_add_u32 v2, v223
	v_max_i32_e32 v2, 0xffffff80, v3
	s_waitcnt vmcnt(19)
	v_add_f32_e32 v3, v13, v13
	v_add_u32_e32 v2, 0x80, v2
	v_cvt_flr_i32_f32_e32 v3, v3
	v_min_u32_e32 v2, 0xff, v2
	v_cndmask_b32_e64 v2, v2, v226, s[4:5]
	v_lshl_add_u32 v2, v2, 2, s6
	ds_add_u32 v2, v223
	v_max_i32_e32 v2, 0xffffff80, v3
	s_waitcnt vmcnt(18)
	v_add_f32_e32 v3, v14, v14
	v_add_u32_e32 v2, 0x80, v2
	v_cvt_flr_i32_f32_e32 v3, v3
	v_min_u32_e32 v2, 0xff, v2
	v_cndmask_b32_e64 v2, v2, v226, s[10:11]
	v_lshl_add_u32 v2, v2, 2, s6
	ds_add_u32 v2, v223
	v_max_i32_e32 v2, 0xffffff80, v3
	s_waitcnt vmcnt(17)
	v_add_f32_e32 v3, v15, v15
	v_add_u32_e32 v2, 0x80, v2
	v_cvt_flr_i32_f32_e32 v3, v3
	v_min_u32_e32 v2, 0xff, v2
	v_cndmask_b32_e64 v2, v2, v226, s[24:25]
	v_lshl_add_u32 v2, v2, 2, s6
	ds_add_u32 v2, v223
	v_max_i32_e32 v2, 0xffffff80, v3
	s_waitcnt vmcnt(16)
	v_add_f32_e32 v3, v16, v16
	v_add_u32_e32 v2, 0x80, v2
	v_cvt_flr_i32_f32_e32 v3, v3
	v_min_u32_e32 v2, 0xff, v2
	v_cndmask_b32_e64 v2, v2, v226, s[26:27]
	v_lshl_add_u32 v2, v2, 2, s6
	ds_add_u32 v2, v223
	v_max_i32_e32 v2, 0xffffff80, v3
	s_waitcnt vmcnt(15)
	v_add_f32_e32 v3, v17, v17
	v_add_u32_e32 v2, 0x80, v2
	v_cvt_flr_i32_f32_e32 v3, v3
	v_min_u32_e32 v2, 0xff, v2
	v_cndmask_b32_e64 v2, v2, v226, s[28:29]
	v_lshl_add_u32 v2, v2, 2, s6
	ds_add_u32 v2, v223
	v_max_i32_e32 v2, 0xffffff80, v3
	s_waitcnt vmcnt(14)
	v_add_f32_e32 v3, v18, v18
	v_add_u32_e32 v2, 0x80, v2
	v_cvt_flr_i32_f32_e32 v3, v3
	v_min_u32_e32 v2, 0xff, v2
	v_cndmask_b32_e64 v2, v2, v226, s[30:31]
	v_lshl_add_u32 v2, v2, 2, s6
	ds_add_u32 v2, v223
	v_max_i32_e32 v2, 0xffffff80, v3
	s_waitcnt vmcnt(13)
	v_add_f32_e32 v3, v19, v19
	v_add_u32_e32 v2, 0x80, v2
	v_cvt_flr_i32_f32_e32 v3, v3
	v_min_u32_e32 v2, 0xff, v2
	v_cndmask_b32_e64 v2, v2, v226, s[34:35]
	v_lshl_add_u32 v2, v2, 2, s6
	ds_add_u32 v2, v223
	v_max_i32_e32 v2, 0xffffff80, v3
	s_waitcnt vmcnt(12)
	v_add_f32_e32 v3, v20, v20
	v_add_u32_e32 v2, 0x80, v2
	v_cvt_flr_i32_f32_e32 v3, v3
	v_min_u32_e32 v2, 0xff, v2
	v_cndmask_b32_e64 v2, v2, v226, s[36:37]
	v_lshl_add_u32 v2, v2, 2, s6
	ds_add_u32 v2, v223
	v_max_i32_e32 v2, 0xffffff80, v3
	s_waitcnt vmcnt(11)
; #define LAS __attribute__((address_space(3)))
; template <int NJ>
; __device__ __forceinline__ void select_rows(const GAS float* sr0, GAS unsigned long long* mb0, LAS unsigned* hist, LAS unsigned* kbuf, int ntl, int lane) {
;     ...
;             const int bk = min(max((int)floorf(f + f) + 128, 0), 255);
;             __hip_atomic_fetch_add(hist + (ok ? bk : 256), 1u, __ATOMIC_RELAXED, __HIP_MEMORY_SCOPE_WORKGROUP);
;         }
;         __builtin_amdgcn_wave_barrier();
;         asm volatile("s_waitcnt lgkmcnt(0)" ::: "memory");
;         unsigned B, rem, C;
;         {
;             const u32x4 hv = *(const LAS u32x4*)(hist + 4 * lane);
;             const unsigned s4 = hv.x + hv.y + hv.z + hv.w;
;             unsigned S = s4;
; #pragma unroll
;             for (int off = 1; off < 64; off <<= 1) { const unsigned n = __shfl_down(S, off); if (lane + off < 64) S += n; }
;             const unsigned excl = S - s4;
;             const bool mine = (excl < 256u) && (256u <= S);
;             unsigned dl, above, cnt, c = excl;
;             if (c + hv.w >= 256u) { dl = 3; above = c; cnt = hv.w; } else { c += hv.w; if (c + hv.z >= 256u) { dl = 2; above = c; cnt = hv.z; } else { c += hv.z; if (c + hv.y >= 256u) { dl = 1; above = c; cnt = hv.y; } else { c += hv.y; dl = 0; above = c; cnt = hv.x; } } }
	v_add_f32_e32 v3, v21, v21
	v_add_u32_e32 v2, 0x80, v2
	v_cvt_flr_i32_f32_e32 v3, v3
	v_min_u32_e32 v2, 0xff, v2
	v_cndmask_b32_e64 v2, v2, v226, s[38:39]
	v_lshl_add_u32 v2, v2, 2, s6
	ds_add_u32 v2, v223
	v_max_i32_e32 v2, 0xffffff80, v3
	s_waitcnt vmcnt(10)
	v_add_f32_e32 v3, v22, v22
	v_add_u32_e32 v2, 0x80, v2
	v_cvt_flr_i32_f32_e32 v3, v3
	v_min_u32_e32 v2, 0xff, v2
	v_cndmask_b32_e64 v2, v2, v226, s[40:41]
	v_lshl_add_u32 v2, v2, 2, s6
	ds_add_u32 v2, v223
	v_max_i32_e32 v2, 0xffffff80, v3
	s_waitcnt vmcnt(9)
	v_add_f32_e32 v3, v23, v23
	v_add_u32_e32 v2, 0x80, v2
	v_cvt_flr_i32_f32_e32 v3, v3
	v_min_u32_e32 v2, 0xff, v2
	v_cndmask_b32_e64 v2, v2, v226, s[42:43]
	v_lshl_add_u32 v2, v2, 2, s6
	ds_add_u32 v2, v223
	v_max_i32_e32 v2, 0xffffff80, v3
	s_waitcnt vmcnt(8)
	v_add_f32_e32 v3, v24, v24
	v_add_u32_e32 v2, 0x80, v2
	v_cvt_flr_i32_f32_e32 v3, v3
	v_min_u32_e32 v2, 0xff, v2
	v_cndmask_b32_e64 v2, v2, v226, s[44:45]
	v_lshl_add_u32 v2, v2, 2, s6
	ds_add_u32 v2, v223
	v_max_i32_e32 v2, 0xffffff80, v3
	s_waitcnt vmcnt(7)
	v_add_f32_e32 v3, v25, v25
	v_add_u32_e32 v2, 0x80, v2
	v_cvt_flr_i32_f32_e32 v3, v3
	v_min_u32_e32 v2, 0xff, v2
	v_cndmask_b32_e64 v2, v2, v226, s[46:47]
	v_lshl_add_u32 v2, v2, 2, s6
	ds_add_u32 v2, v223
	v_max_i32_e32 v2, 0xffffff80, v3
	s_waitcnt vmcnt(6)
	v_add_f32_e32 v3, v26, v26
	v_add_u32_e32 v2, 0x80, v2
	v_cvt_flr_i32_f32_e32 v3, v3
	v_min_u32_e32 v2, 0xff, v2
	v_cndmask_b32_e64 v2, v2, v226, s[48:49]
	v_lshl_add_u32 v2, v2, 2, s6
	ds_add_u32 v2, v223
	v_max_i32_e32 v2, 0xffffff80, v3
	s_waitcnt vmcnt(5)
	v_add_f32_e32 v3, v27, v27
	v_add_u32_e32 v2, 0x80, v2
	v_cvt_flr_i32_f32_e32 v3, v3
	v_min_u32_e32 v2, 0xff, v2
	v_cndmask_b32_e64 v2, v2, v226, s[50:51]
	v_lshl_add_u32 v2, v2, 2, s6
	ds_add_u32 v2, v223
	v_max_i32_e32 v2, 0xffffff80, v3
	s_waitcnt vmcnt(4)
	v_add_f32_e32 v3, v28, v28
	v_add_u32_e32 v2, 0x80, v2
	v_cvt_flr_i32_f32_e32 v3, v3
	v_min_u32_e32 v2, 0xff, v2
	v_cndmask_b32_e64 v2, v2, v226, s[52:53]
	v_lshl_add_u32 v2, v2, 2, s6
	ds_add_u32 v2, v223
	v_max_i32_e32 v2, 0xffffff80, v3
	s_waitcnt vmcnt(3)
	v_add_f32_e32 v3, v29, v29
	v_add_u32_e32 v2, 0x80, v2
	v_cvt_flr_i32_f32_e32 v3, v3
	v_min_u32_e32 v2, 0xff, v2
	v_cndmask_b32_e64 v2, v2, v226, s[64:65]
	v_lshl_add_u32 v2, v2, 2, s6
	ds_add_u32 v2, v223
	v_max_i32_e32 v2, 0xffffff80, v3
	s_waitcnt vmcnt(2)
	v_add_f32_e32 v3, v30, v30
	v_add_u32_e32 v2, 0x80, v2
	v_cvt_flr_i32_f32_e32 v3, v3
	v_min_u32_e32 v2, 0xff, v2
	v_cndmask_b32_e64 v2, v2, v226, s[66:67]
	v_lshl_add_u32 v2, v2, 2, s6
	ds_add_u32 v2, v223
	v_max_i32_e32 v2, 0xffffff80, v3
	s_waitcnt vmcnt(1)
	v_add_f32_e32 v3, v31, v31
	v_add_u32_e32 v2, 0x80, v2
	v_cvt_flr_i32_f32_e32 v3, v3
	v_min_u32_e32 v2, 0xff, v2
	v_cndmask_b32_e64 v2, v2, v226, s[70:71]
	v_lshl_add_u32 v2, v2, 2, s6
	ds_add_u32 v2, v223
	v_max_i32_e32 v2, 0xffffff80, v3
	s_waitcnt vmcnt(0)
	v_add_f32_e32 v3, v32, v32
	v_add_u32_e32 v2, 0x80, v2
	v_cvt_flr_i32_f32_e32 v3, v3
	v_min_u32_e32 v2, 0xff, v2
	v_cndmask_b32_e64 v2, v2, v226, s[72:73]
	v_lshl_add_u32 v2, v2, 2, s6
	ds_add_u32 v2, v223
	v_max_i32_e32 v2, 0xffffff80, v3
	v_add_u32_e32 v2, 0x80, v2
	v_min_u32_e32 v2, 0xff, v2
	v_cndmask_b32_e64 v2, v2, v226, s[76:77]
	v_lshl_add_u32 v2, v2, 2, s6
	ds_add_u32 v2, v223
	s_waitcnt lgkmcnt(0)
	ds_read_b128 v[2:5], v7
	v_readlane_b32 s0, v254, 33
	v_readlane_b32 s1, v254, 34
	s_waitcnt lgkmcnt(0)
	v_add_u32_e32 v34, v2, v3
	v_add3_u32 v35, v34, v4, v5
	v_mov_b32_e32 v34, v35
	s_nop 1
	v_add_u32_dpp v34, v34, v34 row_shr:1 row_mask:0xf bank_mask:0xf bound_ctrl:0
	s_nop 1
	v_add_u32_dpp v34, v34, v34 row_shr:2 row_mask:0xf bank_mask:0xf bound_ctrl:0
	s_nop 1
	v_add_u32_dpp v34, v34, v34 row_shr:4 row_mask:0xf bank_mask:0xf bound_ctrl:0
	s_nop 1
	v_add_u32_dpp v34, v34, v34 row_shr:8 row_mask:0xf bank_mask:0xf bound_ctrl:0
	s_nop 1
	v_add_u32_dpp v34, v34, v34 row_bcast:15 row_mask:0xa bank_mask:0xf
	s_nop 1
	v_add_u32_dpp v34, v34, v34 row_bcast:31 row_mask:0xc bank_mask:0xf
	s_nop 1
	v_readlane_b32 s0, v34, 63
	s_nop 1
	v_sub_u32_e32 v36, s0, v34
	v_add_u32_e32 v34, v36, v35
	v_mov_b32_e32 v35, v36
	v_add_u32_e32 v42, v35, v5
	v_cmp_gt_u32_e32 vcc, s63, v42
	v_mov_b32_e32 v36, 3
	v_mov_b32_e32 v37, v35
	s_and_saveexec_b64 s[0:1], vcc
	s_cbranch_execz .LBB0_539
	v_add_u32_e32 v5, v42, v4
	v_cmp_gt_u32_e32 vcc, s63, v5
	v_mov_b32_e32 v36, 2
	s_and_saveexec_b64 s[2:3], vcc
	v_add_u32_e32 v4, v5, v3
	s_movk_i32 s8, 0xff
	v_cmp_lt_u32_e32 vcc, s8, v4
	s_nop 1
	v_cndmask_b32_e64 v36, 0, 1, vcc
	v_cndmask_b32_e32 v42, v4, v5, vcc
	v_cndmask_b32_e32 v4, v2, v3, vcc
	s_or_b64 exec, exec, s[2:3]
	v_mov_b32_e32 v5, v4
	v_mov_b32_e32 v37, v42

; #define LAS __attribute__((address_space(3)))
; #define GAS __attribute__((address_space(1)))
; __device__ __forceinline__ unsigned skey_of(float f) { const unsigned u = __float_as_uint(f); return u ^ ((unsigned)((int)u >> 31) | 0x80000000u); }
; template <int NJ>
; __device__ __forceinline__ void select_rows(const GAS float* sr0, GAS unsigned long long* mb0, LAS unsigned* hist, LAS unsigned* kbuf, int ntl, int lane) {
;     ...
;     for (int rr = 0; rr < 8; ++rr) {
;         const GAS float* srow = sr0 + (size_t)rr * SEQ;
;         float fv[NJ];
; #pragma unroll
;         for (int j = 0; j < NJ; ++j) fv[j] = srow[64 * j];
;         { unsigned z = 0u; asm volatile("" : "+v"(z));
;           *(LAS u32x4*)(hist + 4 * lane) = (u32x4){z, z, z, z}; if (lane < 2) hist[256 + lane] = z; }
;         __builtin_amdgcn_wave_barrier();
;         unsigned key[NJ];
; #pragma unroll
;         for (int j = 0; j < NJ; ++j) {
;             const float f = fv[j]; const bool ok = (vm >> j) & 1u;
;             key[j] = ok ? skey_of(f) : 0u;
;             const int bk = min(max((int)floorf(f + f) + 128, 0), 255);
;             __hip_atomic_fetch_add(hist + (ok ? bk : 256), 1u, __ATOMIC_RELAXED, __HIP_MEMORY_SCOPE_WORKGROUP);
;         }
;         __builtin_amdgcn_wave_barrier();
;         asm volatile("s_waitcnt lgkmcnt(0)" ::: "memory");
;         unsigned B, rem, C;
;         {
;             const u32x4 hv = *(const LAS u32x4*)(hist + 4 * lane);
;             const unsigned s4 = hv.x + hv.y + hv.z + hv.w;
;             unsigned S = s4;
; #pragma unroll
;             for (int off = 1; off < 64; off <<= 1) { const unsigned n = __shfl_down(S, off); if (lane + off < 64) S += n; }
;             const unsigned excl = S - s4;
;             const bool mine = (excl < 256u) && (256u <= S);
;             unsigned dl, above, cnt, c = excl;
;             if (c + hv.w >= 256u) { dl = 3; above = c; cnt = hv.w; } else { c += hv.w; if (c + hv.z >= 256u) { dl = 2; above = c; cnt = hv.z; } else { c += hv.z; if (c + hv.y >= 256u) { dl = 1; above = c; cnt = hv.y; } else { c += hv.y; dl = 0; above = c; cnt = hv.x; } } }
.LBB0_652:
	s_lshl_b32 s88, s7, 11
	v_lshl_add_u64 v[2:3], s[88:89], 2, v[8:9]
	global_load_dword v25, v[2:3], off
	global_load_dword v10, v[2:3], off offset:256
	global_load_dword v11, v[2:3], off offset:512
	global_load_dword v12, v[2:3], off offset:768
	global_load_dword v13, v[2:3], off offset:1024
	global_load_dword v14, v[2:3], off offset:1280
	global_load_dword v15, v[2:3], off offset:1536
	global_load_dword v16, v[2:3], off offset:1792
	global_load_dword v17, v[2:3], off offset:2048
	global_load_dword v18, v[2:3], off offset:2304
	global_load_dword v19, v[2:3], off offset:2560
	global_load_dword v20, v[2:3], off offset:2816
	global_load_dword v21, v[2:3], off offset:3072
	global_load_dword v22, v[2:3], off offset:3328
	global_load_dword v23, v[2:3], off offset:3584
	global_load_dword v24, v[2:3], off offset:3840
	v_mov_b32_e32 v2, 0
	s_nop 0
	v_mov_b32_e32 v3, v2
	v_mov_b32_e32 v4, v2
	v_mov_b32_e32 v5, v2
	ds_write_b128 v7, v[2:5]
	s_mov_b64 s[8:9], exec
	v_readlane_b32 s38, v254, 15
	v_readlane_b32 s39, v254, 16
	s_and_b64 s[38:39], s[8:9], s[38:39]
	s_mov_b64 exec, s[38:39]
	v_add_u32_e32 v3, v7, v38
	ds_write_b32 v3, v2 offset:1024
	s_or_b64 exec, exec, s[8:9]
	s_waitcnt vmcnt(15)
	v_add_f32_e32 v2, v25, v25
	v_cvt_flr_i32_f32_e32 v2, v2
	s_waitcnt vmcnt(14)
	v_add_f32_e32 v3, v10, v10
	v_cvt_flr_i32_f32_e32 v3, v3
	v_max_i32_e32 v2, 0xffffff80, v2
	v_add_u32_e32 v2, 0x80, v2
	v_min_u32_e32 v2, 0xff, v2
	v_cndmask_b32_e64 v2, v2, v226, s[0:1]
	v_lshl_add_u32 v2, v2, 2, s6
	ds_add_u32 v2, v223
	v_max_i32_e32 v2, 0xffffff80, v3
	s_waitcnt vmcnt(13)
	v_add_f32_e32 v3, v11, v11
	v_add_u32_e32 v2, 0x80, v2
	v_cvt_flr_i32_f32_e32 v3, v3
	v_min_u32_e32 v2, 0xff, v2
	v_cndmask_b32_e64 v2, v2, v226, s[2:3]
	v_lshl_add_u32 v2, v2, 2, s6
	ds_add_u32 v2, v223
	v_max_i32_e32 v2, 0xffffff80, v3
	s_waitcnt vmcnt(12)
	v_add_f32_e32 v3, v12, v12
	v_add_u32_e32 v2, 0x80, v2
	v_cvt_flr_i32_f32_e32 v3, v3
	v_min_u32_e32 v2, 0xff, v2
	v_cndmask_b32_e64 v2, v2, v226, s[4:5]
	v_lshl_add_u32 v2, v2, 2, s6
	ds_add_u32 v2, v223
	v_max_i32_e32 v2, 0xffffff80, v3
	s_waitcnt vmcnt(11)
	v_add_f32_e32 v3, v13, v13
	v_add_u32_e32 v2, 0x80, v2
	v_cvt_flr_i32_f32_e32 v3, v3
	v_min_u32_e32 v2, 0xff, v2
	v_cndmask_b32_e64 v2, v2, v226, s[10:11]
	v_lshl_add_u32 v2, v2, 2, s6
	ds_add_u32 v2, v223
	v_max_i32_e32 v2, 0xffffff80, v3
	s_waitcnt vmcnt(10)
	v_add_f32_e32 v3, v14, v14
	v_add_u32_e32 v2, 0x80, v2
	v_cvt_flr_i32_f32_e32 v3, v3
	v_min_u32_e32 v2, 0xff, v2
	v_cndmask_b32_e64 v2, v2, v226, s[12:13]
	v_lshl_add_u32 v2, v2, 2, s6
	ds_add_u32 v2, v223
	v_max_i32_e32 v2, 0xffffff80, v3
	s_waitcnt vmcnt(9)
	v_add_f32_e32 v3, v15, v15
	v_add_u32_e32 v2, 0x80, v2
	v_cvt_flr_i32_f32_e32 v3, v3
	v_min_u32_e32 v2, 0xff, v2
	v_cndmask_b32_e64 v2, v2, v226, s[14:15]
	v_lshl_add_u32 v2, v2, 2, s6
	ds_add_u32 v2, v223
	v_max_i32_e32 v2, 0xffffff80, v3
	s_waitcnt vmcnt(8)
	v_add_f32_e32 v3, v16, v16
	v_add_u32_e32 v2, 0x80, v2
	v_cvt_flr_i32_f32_e32 v3, v3
	v_min_u32_e32 v2, 0xff, v2
	v_cndmask_b32_e64 v2, v2, v226, s[16:17]
	v_lshl_add_u32 v2, v2, 2, s6
	ds_add_u32 v2, v223
	v_max_i32_e32 v2, 0xffffff80, v3
	s_waitcnt vmcnt(7)
	v_add_f32_e32 v3, v17, v17
	v_add_u32_e32 v2, 0x80, v2
	v_cvt_flr_i32_f32_e32 v3, v3
	v_min_u32_e32 v2, 0xff, v2
	v_cndmask_b32_e64 v2, v2, v226, s[18:19]
	v_lshl_add_u32 v2, v2, 2, s6
	ds_add_u32 v2, v223
	v_max_i32_e32 v2, 0xffffff80, v3
	s_waitcnt vmcnt(6)
	v_add_f32_e32 v3, v18, v18
	v_add_u32_e32 v2, 0x80, v2
	v_cvt_flr_i32_f32_e32 v3, v3
	v_min_u32_e32 v2, 0xff, v2
	v_cndmask_b32_e64 v2, v2, v226, s[52:53]
	v_lshl_add_u32 v2, v2, 2, s6
	ds_add_u32 v2, v223
	v_max_i32_e32 v2, 0xffffff80, v3
	s_waitcnt vmcnt(5)
	v_add_f32_e32 v3, v19, v19
	v_add_u32_e32 v2, 0x80, v2
	v_cvt_flr_i32_f32_e32 v3, v3
	v_min_u32_e32 v2, 0xff, v2
	v_cndmask_b32_e64 v2, v2, v226, s[54:55]
	v_lshl_add_u32 v2, v2, 2, s6
	ds_add_u32 v2, v223
	v_max_i32_e32 v2, 0xffffff80, v3
	s_waitcnt vmcnt(4)
	v_add_f32_e32 v3, v20, v20
	v_add_u32_e32 v2, 0x80, v2
	v_cvt_flr_i32_f32_e32 v3, v3
	v_min_u32_e32 v2, 0xff, v2
	v_cndmask_b32_e64 v2, v2, v226, s[24:25]
	v_lshl_add_u32 v2, v2, 2, s6
	ds_add_u32 v2, v223
	v_max_i32_e32 v2, 0xffffff80, v3
	s_waitcnt vmcnt(3)
	v_add_f32_e32 v3, v21, v21
	v_add_u32_e32 v2, 0x80, v2
	v_cvt_flr_i32_f32_e32 v3, v3
	v_min_u32_e32 v2, 0xff, v2
	v_cndmask_b32_e64 v2, v2, v226, s[26:27]
	v_lshl_add_u32 v2, v2, 2, s6
	ds_add_u32 v2, v223
	v_max_i32_e32 v2, 0xffffff80, v3
	s_waitcnt vmcnt(2)
	v_add_f32_e32 v3, v22, v22
	v_add_u32_e32 v2, 0x80, v2
	v_cvt_flr_i32_f32_e32 v3, v3
	v_min_u32_e32 v2, 0xff, v2
	v_cndmask_b32_e64 v2, v2, v226, s[28:29]
	v_lshl_add_u32 v2, v2, 2, s6
	ds_add_u32 v2, v223
	v_max_i32_e32 v2, 0xffffff80, v3
	s_waitcnt vmcnt(1)
	v_add_f32_e32 v3, v23, v23
	v_add_u32_e32 v2, 0x80, v2
	v_cvt_flr_i32_f32_e32 v3, v3
	v_min_u32_e32 v2, 0xff, v2
	v_cndmask_b32_e64 v2, v2, v226, s[30:31]
	v_lshl_add_u32 v2, v2, 2, s6
	ds_add_u32 v2, v223
	v_max_i32_e32 v2, 0xffffff80, v3
	s_waitcnt vmcnt(0)
	v_add_f32_e32 v3, v24, v24
	v_add_u32_e32 v2, 0x80, v2
	v_cvt_flr_i32_f32_e32 v3, v3
	v_min_u32_e32 v2, 0xff, v2
	v_cndmask_b32_e64 v2, v2, v226, s[34:35]
	v_lshl_add_u32 v2, v2, 2, s6
	ds_add_u32 v2, v223
	v_max_i32_e32 v2, 0xffffff80, v3
	v_add_u32_e32 v2, 0x80, v2
	v_min_u32_e32 v2, 0xff, v2
	v_cndmask_b32_e64 v2, v2, v226, s[36:37]
	v_lshl_add_u32 v2, v2, 2, s6
	ds_add_u32 v2, v223
	s_waitcnt lgkmcnt(0)
	ds_read_b128 v[2:5], v7
	v_readlane_b32 s8, v254, 12
	v_readlane_b32 s9, v254, 13
	s_waitcnt lgkmcnt(0)
	v_add_u32_e32 v26, v2, v3
	v_add3_u32 v27, v26, v4, v5
	v_mov_b32_e32 v26, v27
	s_nop 1
	v_add_u32_dpp v26, v26, v26 row_shr:1 row_mask:0xf bank_mask:0xf bound_ctrl:0
	s_nop 1
	v_add_u32_dpp v26, v26, v26 row_shr:2 row_mask:0xf bank_mask:0xf bound_ctrl:0
	s_nop 1
	v_add_u32_dpp v26, v26, v26 row_shr:4 row_mask:0xf bank_mask:0xf bound_ctrl:0
	s_nop 1
	v_add_u32_dpp v26, v26, v26 row_shr:8 row_mask:0xf bank_mask:0xf bound_ctrl:0
	s_nop 1
	v_add_u32_dpp v26, v26, v26 row_bcast:15 row_mask:0xa bank_mask:0xf
	s_nop 1
	v_add_u32_dpp v26, v26, v26 row_bcast:31 row_mask:0xc bank_mask:0xf
	s_nop 1
	v_readlane_b32 s8, v26, 63
	s_nop 1
	v_sub_u32_e32 v28, s8, v26
	v_add_u32_e32 v26, v28, v27
	v_mov_b32_e32 v27, v28
	v_add_u32_e32 v30, v27, v5
	v_cmp_gt_u32_e32 vcc, s63, v30
	v_mov_b32_e32 v28, 3
	v_mov_b32_e32 v29, v27
	s_and_saveexec_b64 s[8:9], vcc
	s_mov_b32 s88, 0xefa18f08
	s_cbranch_execz .LBB0_658
	v_add_u32_e32 v5, v30, v4
	v_cmp_gt_u32_e32 vcc, s63, v5
	v_mov_b32_e32 v28, 2
	s_and_saveexec_b64 s[38:39], vcc
	v_add_u32_e32 v4, v5, v3
	s_movk_i32 s40, 0xff
	v_cmp_lt_u32_e32 vcc, s40, v4
	s_nop 1
	v_cndmask_b32_e64 v28, 0, 1, vcc
	v_cndmask_b32_e32 v30, v4, v5, vcc
	v_cndmask_b32_e32 v4, v2, v3, vcc
	s_or_b64 exec, exec, s[38:39]
	v_mov_b32_e32 v5, v4
	v_mov_b32_e32 v29, v30

; #define LAS __attribute__((address_space(3)))
; #define GAS __attribute__((address_space(1)))
; __device__ __forceinline__ unsigned skey_of(float f) { const unsigned u = __float_as_uint(f); return u ^ ((unsigned)((int)u >> 31) | 0x80000000u); }
; template <int NJ>
; __device__ __forceinline__ void select_rows(const GAS float* sr0, GAS unsigned long long* mb0, LAS unsigned* hist, LAS unsigned* kbuf, int ntl, int lane) {
;     ...
;     for (int rr = 0; rr < 8; ++rr) {
;         const GAS float* srow = sr0 + (size_t)rr * SEQ;
;         float fv[NJ];
; #pragma unroll
;         for (int j = 0; j < NJ; ++j) fv[j] = srow[64 * j];
;         { unsigned z = 0u; asm volatile("" : "+v"(z));
;           *(LAS u32x4*)(hist + 4 * lane) = (u32x4){z, z, z, z}; if (lane < 2) hist[256 + lane] = z; }
;         __builtin_amdgcn_wave_barrier();
;         unsigned key[NJ];
; #pragma unroll
;         for (int j = 0; j < NJ; ++j) {
;             const float f = fv[j]; const bool ok = (vm >> j) & 1u;
;             key[j] = ok ? skey_of(f) : 0u;
;             const int bk = min(max((int)floorf(f + f) + 128, 0), 255);
;             __hip_atomic_fetch_add(hist + (ok ? bk : 256), 1u, __ATOMIC_RELAXED, __HIP_MEMORY_SCOPE_WORKGROUP);
;         }
;         __builtin_amdgcn_wave_barrier();
;         asm volatile("s_waitcnt lgkmcnt(0)" ::: "memory");
;         unsigned B, rem, C;
;         {
;             const u32x4 hv = *(const LAS u32x4*)(hist + 4 * lane);
;             const unsigned s4 = hv.x + hv.y + hv.z + hv.w;
;             unsigned S = s4;
; #pragma unroll
;             for (int off = 1; off < 64; off <<= 1) { const unsigned n = __shfl_down(S, off); if (lane + off < 64) S += n; }
;             const unsigned excl = S - s4;
;             const bool mine = (excl < 256u) && (256u <= S);
;             unsigned dl, above, cnt, c = excl;
;             if (c + hv.w >= 256u) { dl = 3; above = c; cnt = hv.w; } else { c += hv.w; if (c + hv.z >= 256u) { dl = 2; above = c; cnt = hv.z; } else { c += hv.z; if (c + hv.y >= 256u) { dl = 1; above = c; cnt = hv.y; } else { c += hv.y; dl = 0; above = c; cnt = hv.x; } } }
.LBB0_739:
	s_lshl_b32 s88, s7, 11
	v_lshl_add_u64 v[2:3], s[88:89], 2, v[8:9]
	global_load_dword v17, v[2:3], off
	global_load_dword v10, v[2:3], off offset:256
	global_load_dword v11, v[2:3], off offset:512
	global_load_dword v12, v[2:3], off offset:768
	global_load_dword v13, v[2:3], off offset:1024
	global_load_dword v14, v[2:3], off offset:1280
	global_load_dword v15, v[2:3], off offset:1536
	global_load_dword v16, v[2:3], off offset:1792
	v_mov_b32_e32 v2, 0
	s_nop 0
	v_mov_b32_e32 v3, v2
	v_mov_b32_e32 v4, v2
	v_mov_b32_e32 v5, v2
	ds_write_b128 v7, v[2:5]
	s_and_saveexec_b64 s[8:9], s[74:75]
	v_add_u32_e32 v3, v7, v38
	ds_write_b32 v3, v2 offset:1024
	s_or_b64 exec, exec, s[8:9]
	s_waitcnt vmcnt(7)
	v_add_f32_e32 v2, v17, v17
	v_cvt_flr_i32_f32_e32 v2, v2
	s_waitcnt vmcnt(6)
	v_add_f32_e32 v3, v10, v10
	v_cvt_flr_i32_f32_e32 v3, v3
	v_max_i32_e32 v2, 0xffffff80, v2
	v_add_u32_e32 v2, 0x80, v2
	v_min_u32_e32 v2, 0xff, v2
	v_cndmask_b32_e64 v2, v2, v226, s[0:1]
	v_lshl_add_u32 v2, v2, 2, s6
	ds_add_u32 v2, v223
	v_max_i32_e32 v2, 0xffffff80, v3
	s_waitcnt vmcnt(5)
	v_add_f32_e32 v3, v11, v11
	v_add_u32_e32 v2, 0x80, v2
	v_cvt_flr_i32_f32_e32 v3, v3
	v_min_u32_e32 v2, 0xff, v2
	v_cndmask_b32_e64 v2, v2, v226, s[2:3]
	v_lshl_add_u32 v2, v2, 2, s6
	ds_add_u32 v2, v223
	v_max_i32_e32 v2, 0xffffff80, v3
	s_waitcnt vmcnt(4)
	v_add_f32_e32 v3, v12, v12
	v_add_u32_e32 v2, 0x80, v2
	v_cvt_flr_i32_f32_e32 v3, v3
	v_min_u32_e32 v2, 0xff, v2
	v_cndmask_b32_e64 v2, v2, v226, s[4:5]
	v_lshl_add_u32 v2, v2, 2, s6
	ds_add_u32 v2, v223
	v_max_i32_e32 v2, 0xffffff80, v3
	s_waitcnt vmcnt(3)
	v_add_f32_e32 v3, v13, v13
	v_add_u32_e32 v2, 0x80, v2
	v_cvt_flr_i32_f32_e32 v3, v3
	v_min_u32_e32 v2, 0xff, v2
	v_cndmask_b32_e64 v2, v2, v226, s[10:11]
	v_lshl_add_u32 v2, v2, 2, s6
	ds_add_u32 v2, v223
	v_max_i32_e32 v2, 0xffffff80, v3
	s_waitcnt vmcnt(2)
	v_add_f32_e32 v3, v14, v14
	v_add_u32_e32 v2, 0x80, v2
	v_cvt_flr_i32_f32_e32 v3, v3
	v_min_u32_e32 v2, 0xff, v2
	v_cndmask_b32_e64 v2, v2, v226, s[12:13]
	v_lshl_add_u32 v2, v2, 2, s6
	ds_add_u32 v2, v223
	v_max_i32_e32 v2, 0xffffff80, v3
	s_waitcnt vmcnt(1)
	v_add_f32_e32 v3, v15, v15
	v_add_u32_e32 v2, 0x80, v2
	v_cvt_flr_i32_f32_e32 v3, v3
	v_min_u32_e32 v2, 0xff, v2
	v_cndmask_b32_e64 v2, v2, v226, s[14:15]
	v_lshl_add_u32 v2, v2, 2, s6
	ds_add_u32 v2, v223
	v_max_i32_e32 v2, 0xffffff80, v3
	s_waitcnt vmcnt(0)
	v_add_f32_e32 v3, v16, v16
	v_add_u32_e32 v2, 0x80, v2
	v_cvt_flr_i32_f32_e32 v3, v3
	v_min_u32_e32 v2, 0xff, v2
	v_cndmask_b32_e64 v2, v2, v226, s[16:17]
	v_lshl_add_u32 v2, v2, 2, s6
	ds_add_u32 v2, v223
	v_max_i32_e32 v2, 0xffffff80, v3
	v_add_u32_e32 v2, 0x80, v2
	v_min_u32_e32 v2, 0xff, v2
	v_cndmask_b32_e64 v2, v2, v226, s[18:19]
	v_lshl_add_u32 v2, v2, 2, s6
	ds_add_u32 v2, v223
	s_waitcnt lgkmcnt(0)
	ds_read_b128 v[2:5], v7
	v_readlane_b32 s8, v254, 12
	v_readlane_b32 s9, v254, 13
	s_waitcnt lgkmcnt(0)
	v_add_u32_e32 v18, v2, v3
	v_add3_u32 v19, v18, v4, v5
	v_mov_b32_e32 v18, v19
	s_nop 1
	v_add_u32_dpp v18, v18, v18 row_shr:1 row_mask:0xf bank_mask:0xf bound_ctrl:0
	s_nop 1
	v_add_u32_dpp v18, v18, v18 row_shr:2 row_mask:0xf bank_mask:0xf bound_ctrl:0
	s_nop 1
	v_add_u32_dpp v18, v18, v18 row_shr:4 row_mask:0xf bank_mask:0xf bound_ctrl:0
	s_nop 1
	v_add_u32_dpp v18, v18, v18 row_shr:8 row_mask:0xf bank_mask:0xf bound_ctrl:0
	s_nop 1
	v_add_u32_dpp v18, v18, v18 row_bcast:15 row_mask:0xa bank_mask:0xf
	s_nop 1
	v_add_u32_dpp v18, v18, v18 row_bcast:31 row_mask:0xc bank_mask:0xf
	s_nop 1
	v_readlane_b32 s8, v18, 63
	s_nop 1
	v_sub_u32_e32 v20, s8, v18
	v_add_u32_e32 v18, v20, v19
	v_mov_b32_e32 v19, v20
	v_add_u32_e32 v22, v19, v5
	v_cmp_gt_u32_e32 vcc, s63, v22
	v_mov_b32_e32 v20, 3
	v_mov_b32_e32 v21, v19
	s_and_saveexec_b64 s[8:9], vcc
	s_mov_b32 s88, 0xefa18f08
	s_cbranch_execz .LBB0_745
	v_add_u32_e32 v5, v22, v4
	v_cmp_gt_u32_e32 vcc, s63, v5
	v_mov_b32_e32 v20, 2
	s_and_saveexec_b64 s[48:49], vcc
	v_add_u32_e32 v4, v5, v3
	s_movk_i32 s50, 0xff
	v_cmp_lt_u32_e32 vcc, s50, v4
	s_nop 1
	v_cndmask_b32_e64 v20, 0, 1, vcc
	v_cndmask_b32_e32 v22, v4, v5, vcc
	v_cndmask_b32_e32 v4, v2, v3, vcc
	s_or_b64 exec, exec, s[48:49]
	v_mov_b32_e32 v5, v4
	v_mov_b32_e32 v21, v22
